# adds to previous: same LDS tile row permutation for the two P0 W_in transpose paths (8-way bank conflict on transposed reads removed)
# baseline (speedup 1.0000x reference)
; #define LAS __attribute__((address_space(3)))
; #define g_mix ARGP(2)
; #define w_in ARGP(3)
; __device__ __forceinline__ void p0_transpose64(const float* W, int ldw, int K, const float* gain, bf16_t* WT, int nblk, int ncol_src0, int row_off, LAS float* scr, int item, int lane) {
;     const int kb = item / nblk, nb = item % nblk, k0 = 64 * kb, n0 = 64 * nb;
;     const int c4 = (lane & 15) * 4, kr = lane >> 4;
; __global__ void __launch_bounds__(NWAVES * 64, 2) fwd(Args args) {
;     ...
;         } else {
;             constexpr int I_INL = (DM / 64) * (IN_Q0 / 64);
;             for (int it = (bx - NQB) * NWAVES + F.wave; it < I_INL; it += (256 - NQB) * NWAVES) { const int kb = it / (IN_Q0 / 64), nb = it % (IN_Q0 / 64);
;                 p0_transpose64(w_in, INW, DM, g_mix, W_inT, IN_N / 64, (nb * 64 >= 4096) ? 16 : 0, 0, scr, kb * (IN_N / 64) + nb, F.lane); }
.LBB0_11:
	s_or_b64 exec, exec, s[0:1]
	v_readlane_b32 s0, v254, 0
	s_lshr_b32 s46, s0, 6
	s_add_u32 s72, s78, 0x800000
	s_addc_u32 s73, s79, 0
	s_lshl_b32 s57, s94, 3
	s_add_i32 s82, s57, s46
	s_lshl_b32 s68, s88, 3
	s_cmp_lt_i32 s96, 1
	s_cselect_b64 s[0:1], -1, 0
	s_cmp_gt_i32 s97, 0
	s_cselect_b64 s[4:5], -1, 0
	s_and_b64 s[0:1], s[0:1], s[4:5]
	s_andn2_b64 vcc, exec, s[0:1]
	v_and_b32_e32 v182, 63, v0
	s_cbranch_vccnz .LBB0_90
	s_mul_i32 s3, s46, 0x4400
	s_add_i32 s14, s3, 0
	s_cmpk_gt_i32 s2, 0x5f
	s_cselect_b64 s[8:9], -1, 0
	s_mov_b64 s[4:5], -1
	s_and_b64 vcc, exec, s[8:9]
	s_cbranch_vccz .LBB0_49
	s_lshl_b32 s3, s2, 3
	s_add_i32 s3, s3, s46
	s_addk_i32 s3, 0xfd00
	s_cmpk_gt_i32 s3, 0x17ff
	s_cbranch_scc1 .LBB0_48
	v_lshlrev_b32_e32 v5, 3, v0
	v_and_b32_e32 v2, 60, v1
	v_lshrrev_b32_e32 v74, 4, v182
	v_and_b32_e32 v5, 56, v5
	v_lshrrev_b32_e32 v75, 3, v182
	v_mov_b32_e32 v67, 0
	v_lshl_add_u32 v3, v2, 2, s14
	v_mul_u32_u24_e32 v4, 0x110, v74
	v_mul_u32_u24_e32 v6, 0x110, v5
	v_lshlrev_b32_e32 v66, 1, v5
	v_lshlrev_b32_e32 v5, 2, v75
	v_lshl_add_u64 v[68:69], s[72:73], 0, v[66:67]
	v_add3_u32 v76, s14, v6, v5
	v_and_b32_e32 v248, 7, v182
	v_mul_u32_u24_e32 v248, 0x770, v248
	v_sub_u32_e32 v76, v76, v248
	v_or_b32_e32 v77, 8, v75
	v_or_b32_e32 v78, 16, v75
	v_or_b32_e32 v79, 24, v75
	v_or_b32_e32 v80, 32, v75
	v_or_b32_e32 v81, 40, v75
	v_or_b32_e32 v82, 48, v75
	v_or_b32_e32 v83, 56, v75
	v_mov_b64_e32 v[70:71], s[92:93]
	s_mov_b32 s5, 0
	v_lshlrev_b32_e32 v66, 2, v2
	s_mov_b32 s15, 0xc040
	v_add_u32_e32 v84, v3, v4
	v_lshrrev_b32_e32 v248, 4, v182
	v_mul_u32_u24_e32 v248, 0x770, v248
	v_add_u32_e32 v84, v84, v248
	s_branch .LBB0_16
; #define GAS __attribute__((address_space(1)))
; #define LAS __attribute__((address_space(3)))
; __device__ __forceinline__ unsigned cvt_pk_bf16(float lo, float hi) { unsigned r; asm volatile("v_cvt_pk_bf16_f32 %0, %1, %2" : "=v"(r) : "v"(lo), "v"(hi)); return r; }
; #define LDS_WAIT() asm volatile("s_waitcnt lgkmcnt(0)" ::: "memory")
; #define g_mix ARGP(2)
; #define w_in ARGP(3)
; __device__ __forceinline__ void p0_transpose64(const float* W, int ldw, int K, const float* gain, bf16_t* WT, int nblk, int ncol_src0, int row_off, LAS float* scr, int item, int lane) {
;     ...
;     for (int j = 0; j < 8; ++j) { const int idx = lane + 64 * j, n = idx >> 3, c = idx & 7; const LAS float* sp = scr + (8 * c) * 68 + n;
;         u32x4 o; o.x = cvt_pk_bf16(sp[0 * 68], sp[1 * 68]); o.y = cvt_pk_bf16(sp[2 * 68], sp[3 * 68]); o.z = cvt_pk_bf16(sp[4 * 68], sp[5 * 68]); o.w = cvt_pk_bf16(sp[6 * 68], sp[7 * 68]);
;         *(GAS u32x4*)(WT + (size_t)(row_off + n0 + n) * K + k0 + 8 * c) = o; }
;     LDS_WAIT(); asm volatile("" ::: "memory");
; __global__ void __launch_bounds__(NWAVES * 64, 2) fwd(Args args) {
;     ...
;             for (int it = (bx - NQB) * NWAVES + F.wave; it < I_INL; it += (256 - NQB) * NWAVES) { const int kb = it / (IN_Q0 / 64), nb = it % (IN_Q0 / 64);
;                 p0_transpose64(w_in, INW, DM, g_mix, W_inT, IN_N / 64, (nb * 64 >= 4096) ? 16 : 0, 0, scr, kb * (IN_N / 64) + nb, F.lane); }
.LBB0_15:
	s_or_b64 exec, exec, s[12:13]
	ds_write_b128 v84, v[2:5] offset:10608
	s_waitcnt lgkmcnt(0)
	v_or_b32_e32 v8, s6, v75
	ds_read_b32 v2, v76
	ds_read_b32 v3, v76 offset:2176
	s_ashr_i32 s11, s10, 31
	v_ashrrev_i32_e32 v9, 31, v8
	s_waitcnt lgkmcnt(0)
	v_cvt_pk_bf16_f32 v2, v2, v3
	ds_read_b32 v4, v76 offset:4352
	ds_read_b32 v5, v76 offset:6528
	v_add_u32_e32 v12, 0x400, v76
	v_lshl_add_u64 v[10:11], s[10:11], 1, v[68:69]
	v_lshlrev_b64 v[8:9], 13, v[8:9]
	s_waitcnt lgkmcnt(0)
	v_cvt_pk_bf16_f32 v3, v4, v5
	ds_read_b32 v4, v76 offset:8704
	ds_read_b32 v5, v76 offset:10880
	v_lshl_add_u64 v[8:9], v[10:11], 0, v[8:9]
	s_waitcnt lgkmcnt(0)
	v_cvt_pk_bf16_f32 v4, v4, v5
	ds_read_b32 v6, v76 offset:13056
	ds_read_b32 v7, v76 offset:15232
	s_waitcnt lgkmcnt(0)
	v_cvt_pk_bf16_f32 v5, v6, v7
	global_store_dwordx4 v[8:9], v[2:5], off
	v_or_b32_e32 v8, s6, v77
	v_ashrrev_i32_e32 v9, 31, v8
	ds_read_b32 v6, v76 offset:32
	ds_read_b32 v7, v76 offset:2208
	s_waitcnt lgkmcnt(0)
	v_cvt_pk_bf16_f32 v2, v6, v7
	ds_read_b32 v4, v76 offset:4384
	ds_read_b32 v5, v76 offset:6560
	v_lshlrev_b64 v[8:9], 13, v[8:9]
	s_waitcnt lgkmcnt(0)
	v_cvt_pk_bf16_f32 v3, v4, v5
	ds_read_b32 v4, v76 offset:8736
	ds_read_b32 v5, v76 offset:10912
	v_lshl_add_u64 v[8:9], v[10:11], 0, v[8:9]
	s_waitcnt lgkmcnt(0)
	v_cvt_pk_bf16_f32 v4, v4, v5
	ds_read_b32 v6, v76 offset:13088
	ds_read_b32 v7, v76 offset:15264
	s_waitcnt lgkmcnt(0)
	v_cvt_pk_bf16_f32 v5, v6, v7
	global_store_dwordx4 v[8:9], v[2:5], off
	v_or_b32_e32 v8, s6, v78
	v_ashrrev_i32_e32 v9, 31, v8
	ds_read_b32 v6, v76 offset:64
	ds_read_b32 v7, v76 offset:2240
	s_waitcnt lgkmcnt(0)
	v_cvt_pk_bf16_f32 v2, v6, v7
	ds_read_b32 v4, v76 offset:4416
	ds_read_b32 v5, v76 offset:6592
	v_lshlrev_b64 v[8:9], 13, v[8:9]
	s_waitcnt lgkmcnt(0)
	v_cvt_pk_bf16_f32 v3, v4, v5
	ds_read_b32 v4, v76 offset:8768
	ds_read_b32 v5, v76 offset:10944
	v_lshl_add_u64 v[8:9], v[10:11], 0, v[8:9]
	s_waitcnt lgkmcnt(0)
	v_cvt_pk_bf16_f32 v4, v4, v5
	ds_read_b32 v6, v76 offset:13120
	ds_read_b32 v7, v76 offset:15296
	s_waitcnt lgkmcnt(0)
	v_cvt_pk_bf16_f32 v5, v6, v7
	global_store_dwordx4 v[8:9], v[2:5], off
	v_or_b32_e32 v8, s6, v79
	v_ashrrev_i32_e32 v9, 31, v8
	ds_read_b32 v6, v76 offset:96
	ds_read_b32 v7, v76 offset:2272
	s_waitcnt lgkmcnt(0)
	v_cvt_pk_bf16_f32 v2, v6, v7
	ds_read_b32 v4, v76 offset:4448
	ds_read_b32 v5, v76 offset:6624
	v_lshlrev_b64 v[8:9], 13, v[8:9]
	s_waitcnt lgkmcnt(0)
	v_cvt_pk_bf16_f32 v3, v4, v5
	ds_read_b32 v4, v76 offset:8800
	ds_read_b32 v5, v76 offset:10976
	v_lshl_add_u64 v[8:9], v[10:11], 0, v[8:9]
	s_waitcnt lgkmcnt(0)
	v_cvt_pk_bf16_f32 v4, v4, v5
	ds_read_b32 v6, v76 offset:13152
	ds_read_b32 v7, v76 offset:15328
	s_waitcnt lgkmcnt(0)
	v_cvt_pk_bf16_f32 v5, v6, v7
	global_store_dwordx4 v[8:9], v[2:5], off
	v_or_b32_e32 v8, s6, v80
	v_ashrrev_i32_e32 v9, 31, v8
	ds_read_b32 v6, v76 offset:128
	ds_read_b32 v7, v76 offset:2304
	s_waitcnt lgkmcnt(0)
	v_cvt_pk_bf16_f32 v2, v6, v7
	ds_read_b32 v4, v76 offset:4480
	ds_read_b32 v5, v76 offset:6656
	v_lshlrev_b64 v[8:9], 13, v[8:9]
	s_waitcnt lgkmcnt(0)
	v_cvt_pk_bf16_f32 v3, v4, v5
	ds_read_b32 v4, v76 offset:8832
	ds_read_b32 v5, v76 offset:11008
	v_lshl_add_u64 v[8:9], v[10:11], 0, v[8:9]
	s_waitcnt lgkmcnt(0)
	v_cvt_pk_bf16_f32 v4, v4, v5
	ds_read_b32 v6, v76 offset:13184
	ds_read_b32 v7, v76 offset:15360
	s_waitcnt lgkmcnt(0)
	v_cvt_pk_bf16_f32 v5, v6, v7
	global_store_dwordx4 v[8:9], v[2:5], off
	v_or_b32_e32 v8, s6, v81
	v_ashrrev_i32_e32 v9, 31, v8
	ds_read_b32 v6, v76 offset:160
	ds_read_b32 v7, v76 offset:2336
	s_waitcnt lgkmcnt(0)
	v_cvt_pk_bf16_f32 v2, v6, v7
	ds_read_b32 v4, v76 offset:4512
	ds_read_b32 v5, v76 offset:6688
	v_lshlrev_b64 v[8:9], 13, v[8:9]
	s_waitcnt lgkmcnt(0)
	v_cvt_pk_bf16_f32 v3, v4, v5
	ds_read_b32 v4, v76 offset:8864
	ds_read_b32 v5, v76 offset:11040
	v_add_u32_e32 v13, 0x600, v76
	v_lshl_add_u64 v[8:9], v[10:11], 0, v[8:9]
	s_waitcnt lgkmcnt(0)
	v_cvt_pk_bf16_f32 v4, v4, v5
	ds_read_b32 v6, v76 offset:13216
	ds_read_b32 v7, v76 offset:15392
	s_waitcnt lgkmcnt(0)
	v_cvt_pk_bf16_f32 v5, v6, v7
	global_store_dwordx4 v[8:9], v[2:5], off
	v_or_b32_e32 v8, s6, v82
	ds_read_b32 v6, v76 offset:192
	ds_read_b32 v7, v76 offset:2368
	s_waitcnt lgkmcnt(0)
	v_cvt_pk_bf16_f32 v2, v6, v7
	ds_read_b32 v4, v76 offset:4544
	ds_read_b32 v5, v76 offset:6720
	v_ashrrev_i32_e32 v9, 31, v8
	s_waitcnt lgkmcnt(0)
	v_cvt_pk_bf16_f32 v3, v4, v5
	ds_read_b32 v4, v76 offset:8896
	ds_read_b32 v5, v76 offset:11072
	v_lshlrev_b64 v[8:9], 13, v[8:9]
	s_waitcnt lgkmcnt(0)
	v_cvt_pk_bf16_f32 v4, v4, v5
	ds_read_b32 v6, v76 offset:13248
	ds_read_b32 v7, v76 offset:15424
	v_add_u32_e32 v14, 0x200, v76
	s_waitcnt lgkmcnt(0)
	v_cvt_pk_bf16_f32 v5, v6, v7
	v_lshl_add_u64 v[8:9], v[10:11], 0, v[8:9]
	ds_read_b32 v6, v76 offset:224
	ds_read_b32 v7, v76 offset:2400
	global_store_dwordx4 v[8:9], v[2:5], off
	v_or_b32_e32 v8, s6, v83
	v_ashrrev_i32_e32 v9, 31, v8
	s_waitcnt lgkmcnt(0)
	v_cvt_pk_bf16_f32 v2, v6, v7
	ds_read_b32 v4, v76 offset:4576
	ds_read_b32 v5, v76 offset:6752
	s_waitcnt lgkmcnt(0)
	v_cvt_pk_bf16_f32 v3, v4, v5
	ds_read_b32 v4, v76 offset:8928
	ds_read_b32 v5, v76 offset:11104
	s_waitcnt lgkmcnt(0)
	v_cvt_pk_bf16_f32 v4, v4, v5
	ds_read_b32 v6, v76 offset:13280
	ds_read_b32 v7, v76 offset:15456
	v_lshlrev_b64 v[8:9], 13, v[8:9]
	s_waitcnt lgkmcnt(0)
	v_cvt_pk_bf16_f32 v5, v6, v7
	v_lshl_add_u64 v[6:7], v[10:11], 0, v[8:9]
	global_store_dwordx4 v[6:7], v[2:5], off
	s_waitcnt lgkmcnt(0)
	s_add_i32 s4, s3, 0x500
	s_cmpk_lt_i32 s3, 0x1300
	s_mov_b32 s3, s4
	s_cbranch_scc0 .LBB0_48

; #define LAS __attribute__((address_space(3)))
; __device__ __forceinline__ void p0_transpose64(const float* W, int ldw, int K, const float* gain, bf16_t* WT, int nblk, int ncol_src0, int row_off, LAS float* scr, int item, int lane) {
;     ...
;     for (int i = 0; i < 16; ++i) w[i] = __builtin_nontemporal_load((const f32x4*)(W + (size_t)(k0 + kr + 4 * i) * ldw + ncol_src0 + n0 + c4));
; #pragma unroll
;     for (int i = 0; i < 16; ++i) { f32x4 v = w[i]; if (gain) v = v * gain[k0 + kr + 4 * i]; *(LAS f32x4*)(scr + (kr + 4 * i) * 68 + c4) = v; }
.LBB0_20:
	s_or_b64 exec, exec, s[12:13]
	s_waitcnt vmcnt(0) lgkmcnt(0)
	ds_write_b128 v84, v[58:61] offset:8704
	s_and_saveexec_b64 s[12:13], vcc
	s_xor_b64 s[12:13], exec, s[12:13]
	s_cbranch_execz .LBB0_22
	flat_load_dword v58, v[72:73] offset:32
	s_waitcnt vmcnt(0) lgkmcnt(0)
	v_pk_mul_f32 v[56:57], v[56:57], v[58:59] op_sel_hi:[1,0]
	v_pk_mul_f32 v[54:55], v[54:55], v[58:59] op_sel_hi:[1,0]
	ds_write_b128 v84, v[54:57] offset:272
	flat_load_dword v54, v[72:73] offset:48
	s_waitcnt vmcnt(0) lgkmcnt(0)
	v_pk_mul_f32 v[52:53], v[52:53], v[54:55] op_sel_hi:[1,0]
	v_pk_mul_f32 v[50:51], v[50:51], v[54:55] op_sel_hi:[1,0]
.LBB0_22:
	s_andn2_saveexec_b64 s[12:13], s[12:13]
	ds_write_b128 v84, v[54:57] offset:272
	s_or_b64 exec, exec, s[12:13]
	ds_write_b128 v84, v[50:53] offset:8976
	s_and_saveexec_b64 s[12:13], vcc
	s_xor_b64 s[12:13], exec, s[12:13]
	s_cbranch_execz .LBB0_26
	flat_load_dword v50, v[72:73] offset:64
	s_waitcnt vmcnt(0) lgkmcnt(0)
	v_pk_mul_f32 v[48:49], v[48:49], v[50:51] op_sel_hi:[1,0]
	v_pk_mul_f32 v[46:47], v[46:47], v[50:51] op_sel_hi:[1,0]
	ds_write_b128 v84, v[46:49] offset:544
	flat_load_dword v46, v[72:73] offset:80
	s_waitcnt vmcnt(0) lgkmcnt(0)
	v_pk_mul_f32 v[44:45], v[44:45], v[46:47] op_sel_hi:[1,0]
	v_pk_mul_f32 v[42:43], v[42:43], v[46:47] op_sel_hi:[1,0]
.LBB0_26:
	s_andn2_saveexec_b64 s[12:13], s[12:13]
	ds_write_b128 v84, v[46:49] offset:544
	s_or_b64 exec, exec, s[12:13]
	ds_write_b128 v84, v[42:45] offset:9248
	s_and_saveexec_b64 s[12:13], vcc
	s_xor_b64 s[12:13], exec, s[12:13]
	s_cbranch_execz .LBB0_30
	flat_load_dword v42, v[72:73] offset:96
	s_waitcnt vmcnt(0) lgkmcnt(0)
	v_pk_mul_f32 v[40:41], v[40:41], v[42:43] op_sel_hi:[1,0]
	v_pk_mul_f32 v[38:39], v[38:39], v[42:43] op_sel_hi:[1,0]
	ds_write_b128 v84, v[38:41] offset:816
	flat_load_dword v38, v[72:73] offset:112
	s_waitcnt vmcnt(0) lgkmcnt(0)
	v_pk_mul_f32 v[36:37], v[36:37], v[38:39] op_sel_hi:[1,0]
	v_pk_mul_f32 v[34:35], v[34:35], v[38:39] op_sel_hi:[1,0]
.LBB0_30:
	s_andn2_saveexec_b64 s[12:13], s[12:13]
	ds_write_b128 v84, v[38:41] offset:816
	s_or_b64 exec, exec, s[12:13]
	ds_write_b128 v84, v[34:37] offset:9520
	s_and_saveexec_b64 s[12:13], vcc
	s_xor_b64 s[12:13], exec, s[12:13]
	s_cbranch_execz .LBB0_34
	flat_load_dword v34, v[72:73] offset:128
	s_waitcnt vmcnt(0) lgkmcnt(0)
	v_pk_mul_f32 v[32:33], v[32:33], v[34:35] op_sel_hi:[1,0]
	v_pk_mul_f32 v[30:31], v[30:31], v[34:35] op_sel_hi:[1,0]
	ds_write_b128 v84, v[30:33] offset:1088
	flat_load_dword v30, v[72:73] offset:144
	s_waitcnt vmcnt(0) lgkmcnt(0)
	v_pk_mul_f32 v[28:29], v[28:29], v[30:31] op_sel_hi:[1,0]
	v_pk_mul_f32 v[26:27], v[26:27], v[30:31] op_sel_hi:[1,0]
.LBB0_34:
	s_andn2_saveexec_b64 s[12:13], s[12:13]
	ds_write_b128 v84, v[30:33] offset:1088
	s_or_b64 exec, exec, s[12:13]
	ds_write_b128 v84, v[26:29] offset:9792
	s_and_saveexec_b64 s[12:13], vcc
	s_xor_b64 s[12:13], exec, s[12:13]
	s_cbranch_execz .LBB0_38
	flat_load_dword v26, v[72:73] offset:160
	s_waitcnt vmcnt(0) lgkmcnt(0)
	v_pk_mul_f32 v[24:25], v[24:25], v[26:27] op_sel_hi:[1,0]
	v_pk_mul_f32 v[22:23], v[22:23], v[26:27] op_sel_hi:[1,0]
	ds_write_b128 v84, v[22:25] offset:1360
	flat_load_dword v22, v[72:73] offset:176
	s_waitcnt vmcnt(0) lgkmcnt(0)
	v_pk_mul_f32 v[20:21], v[20:21], v[22:23] op_sel_hi:[1,0]
	v_pk_mul_f32 v[18:19], v[18:19], v[22:23] op_sel_hi:[1,0]
.LBB0_38:
	s_andn2_saveexec_b64 s[12:13], s[12:13]
	ds_write_b128 v84, v[22:25] offset:1360
	s_or_b64 exec, exec, s[12:13]
	ds_write_b128 v84, v[18:21] offset:10064
	s_and_saveexec_b64 s[12:13], vcc
	s_xor_b64 s[12:13], exec, s[12:13]
	s_cbranch_execz .LBB0_42
	flat_load_dword v18, v[72:73] offset:192
	s_waitcnt vmcnt(0) lgkmcnt(0)
	v_pk_mul_f32 v[16:17], v[16:17], v[18:19] op_sel_hi:[1,0]
	v_pk_mul_f32 v[14:15], v[14:15], v[18:19] op_sel_hi:[1,0]
	ds_write_b128 v84, v[14:17] offset:1632
	flat_load_dword v14, v[72:73] offset:208
	s_waitcnt vmcnt(0) lgkmcnt(0)
	v_pk_mul_f32 v[12:13], v[12:13], v[14:15] op_sel_hi:[1,0]
	v_pk_mul_f32 v[10:11], v[10:11], v[14:15] op_sel_hi:[1,0]
.LBB0_42:
	s_andn2_saveexec_b64 s[12:13], s[12:13]
	ds_write_b128 v84, v[14:17] offset:1632
	s_or_b64 exec, exec, s[12:13]
	ds_write_b128 v84, v[10:13] offset:10336
	s_and_saveexec_b64 s[12:13], vcc
	s_xor_b64 s[12:13], exec, s[12:13]
	s_cbranch_execz .LBB0_46
	flat_load_dword v10, v[72:73] offset:224
	s_waitcnt vmcnt(0) lgkmcnt(0)
	v_pk_mul_f32 v[8:9], v[8:9], v[10:11] op_sel_hi:[1,0]
	v_pk_mul_f32 v[6:7], v[6:7], v[10:11] op_sel_hi:[1,0]
	ds_write_b128 v84, v[6:9] offset:1904
	flat_load_dword v6, v[72:73] offset:240
	s_waitcnt vmcnt(0) lgkmcnt(0)
	v_pk_mul_f32 v[4:5], v[4:5], v[6:7] op_sel_hi:[1,0]
	v_pk_mul_f32 v[2:3], v[2:3], v[6:7] op_sel_hi:[1,0]
.LBB0_46:
	s_andn2_saveexec_b64 s[12:13], s[12:13]
	s_cbranch_execz .LBB0_15
	ds_write_b128 v84, v[6:9] offset:1904
	s_branch .LBB0_15

; #define g_mix ARGP(2)
; #define w_in ARGP(3)
; __device__ __forceinline__ void p0_load(const P0Item& it, f32x4 (&w)[16], int lane) {
;     const unsigned voff = (unsigned)(((lane >> 4) * it.ldw + (lane & 15) * 4) * 4);
; #pragma unroll
;     for (int i = 0; i < 16; ++i) w[i] = __builtin_nontemporal_load((const f32x4*)((const char*)(it.src + (size_t)(4 * i) * it.ldw) + voff));
; }
; __global__ void __launch_bounds__(NWAVES * 64, 2) fwd(Args args) {
;     ...
;         if (bx < NQB) {
;             const int nb = IN_Q0 / 64 + bx, src0 = (nb * 64 >= 4096) ? 16 : 0;
;             { const float* wsrc = w_in; const float* gsrc = g_mix; const int wv = F.wave;
;               p0_pipe(8, [&](int i) { return p0_item(wsrc, INW, DM, gsrc, W_inT, IN_N / 64, src0, 0, (wv + 8 * i) * (IN_N / 64) + nb); }, scr, F.lane); }
.LBB0_49:
	s_andn2_b64 vcc, exec, s[4:5]
	s_cbranch_vccnz .LBB0_66
	v_mov_b64_e32 v[2:3], s[92:93]
	flat_load_dwordx2 v[66:67], v[2:3] offset:24 sc0 sc1
	s_waitcnt vmcnt(0)
	s_cmpk_gt_i32 s2, 0xffdf
	s_mul_i32 s4, s46, 0xc0
	s_cselect_b32 s10, 64, 0
	s_add_i32 s15, s2, s4
	s_add_i32 s4, s15, 0x60
	s_mul_hi_i32 s5, s4, 0x2aaaaaab
	s_lshr_b32 s6, s5, 31
	s_ashr_i32 s5, s5, 5
	s_add_i32 s5, s5, s6
	v_lshrrev_b32_e32 v90, 4, v182
	s_mul_i32 s7, s5, 0xc0
	v_mov_b32_e32 v148, 0xc040
	v_and_b32_e32 v91, 60, v1
	flat_load_dwordx2 v[136:137], v[2:3] offset:16 sc0 sc1
	s_waitcnt vmcnt(0)
	v_mul_u32_u24_e32 v2, 0x3010, v90
	s_lshl_b32 s6, s5, 6
	s_sub_i32 s4, s4, s7
	s_mov_b32 s11, 0
	v_add_lshl_u32 v134, v2, v91, 2
	s_lshl_b32 s4, s4, 6
	s_ashr_i32 s5, s4, 31
	v_mov_b32_e32 v135, 0
	s_mov_b32 s3, 0x30000
	s_mov_b32 s22, 0x60000
	s_mov_b32 s23, 0x90000
	s_mov_b32 s24, 0xc0000
	s_mov_b32 s25, 0xf0000
	s_mov_b32 s26, 0x120000
	s_mov_b32 s27, 0x150000
	s_mov_b32 s28, 0x180000
	s_mov_b32 s29, 0x1b0000
	s_mov_b32 s30, 0x1e0000
	s_mov_b32 s31, 0x210000
	s_mov_b32 s33, 0x240000
	s_mov_b32 s7, 0x270000
	v_lshlrev_b32_e32 v138, 2, v90
	v_mov_b32_e32 v139, v135
	v_mov_b32_e32 v141, v135
	s_mov_b32 s34, 0x10000
	s_mov_b32 s35, 0x20000
	s_mov_b32 s36, 0x40000
	s_mov_b32 s37, 0x50000
	s_waitcnt lgkmcnt(0)
	v_mad_i64_i32 v[2:3], s[12:13], s6, v148, v[66:67]
	v_lshl_add_u64 v[2:3], v[2:3], 0, s[10:11]
	v_lshl_add_u64 v[2:3], s[4:5], 2, v[2:3]
	v_lshl_add_u64 v[18:19], v[2:3], 0, v[134:135]
	v_add_co_u32_e32 v20, vcc, s3, v18
	s_lshl_b64 s[4:5], s[4:5], 13
	s_nop 0
	v_addc_co_u32_e32 v21, vcc, 0, v19, vcc
	v_add_co_u32_e32 v22, vcc, s22, v18
	v_lshl_add_u64 v[142:143], v[66:67], 0, s[10:11]
	s_nop 0
	v_addc_co_u32_e32 v23, vcc, 0, v19, vcc
	v_add_co_u32_e32 v24, vcc, s23, v18
	v_lshl_add_u64 v[144:145], v[136:137], 0, v[138:139]
	s_nop 0
	v_addc_co_u32_e32 v25, vcc, 0, v19, vcc
	v_add_co_u32_e32 v26, vcc, s24, v18
	flat_load_dwordx4 v[2:5], v[18:19] nt
	flat_load_dwordx4 v[6:9], v[20:21] offset:256 nt
	flat_load_dwordx4 v[10:13], v[22:23] offset:512 nt
	flat_load_dwordx4 v[14:17], v[24:25] offset:768 nt
	v_addc_co_u32_e32 v27, vcc, 0, v19, vcc
	v_add_co_u32_e32 v68, vcc, s25, v18
	s_nop 1
	v_addc_co_u32_e32 v69, vcc, 0, v19, vcc
	v_add_co_u32_e32 v70, vcc, s26, v18
	s_nop 1
	v_addc_co_u32_e32 v71, vcc, 0, v19, vcc
	v_add_co_u32_e32 v72, vcc, s27, v18
	s_nop 1
	v_addc_co_u32_e32 v73, vcc, 0, v19, vcc
	v_add_co_u32_e32 v74, vcc, s28, v18
	s_nop 1
	v_addc_co_u32_e32 v75, vcc, 0, v19, vcc
	v_add_co_u32_e32 v76, vcc, s29, v18
	s_nop 1
	v_addc_co_u32_e32 v77, vcc, 0, v19, vcc
	v_add_co_u32_e32 v78, vcc, s30, v18
	s_nop 1
	v_addc_co_u32_e32 v79, vcc, 0, v19, vcc
	v_add_co_u32_e32 v80, vcc, s31, v18
	s_nop 1
	v_addc_co_u32_e32 v81, vcc, 0, v19, vcc
	v_add_co_u32_e32 v82, vcc, s33, v18
	s_nop 1
	v_addc_co_u32_e32 v83, vcc, 0, v19, vcc
	v_add_co_u32_e32 v84, vcc, s7, v18
	s_mov_b32 s7, 0x2a0000
	s_nop 0
	v_addc_co_u32_e32 v85, vcc, 0, v19, vcc
	v_add_co_u32_e32 v86, vcc, s7, v18
	s_mov_b32 s7, 0x2d0000
	s_nop 0
	v_addc_co_u32_e32 v87, vcc, 0, v19, vcc
	v_add_co_u32_e32 v88, vcc, s7, v18
	s_ashr_i32 s7, s6, 31
	s_nop 0
	v_addc_co_u32_e32 v89, vcc, 0, v19, vcc
	flat_load_dwordx4 v[18:21], v[26:27] offset:1024 nt
	flat_load_dwordx4 v[22:25], v[68:69] offset:1280 nt
	s_nop 0
	flat_load_dwordx4 v[26:29], v[70:71] offset:1536 nt
	flat_load_dwordx4 v[30:33], v[72:73] offset:1792 nt
	flat_load_dwordx4 v[34:37], v[74:75] offset:2048 nt
	flat_load_dwordx4 v[38:41], v[76:77] offset:2304 nt
	flat_load_dwordx4 v[42:45], v[78:79] offset:2560 nt
	flat_load_dwordx4 v[46:49], v[80:81] offset:2816 nt
	flat_load_dwordx4 v[50:53], v[82:83] offset:3072 nt
	flat_load_dwordx4 v[54:57], v[84:85] offset:3328 nt
	flat_load_dwordx4 v[58:61], v[86:87] offset:3584 nt
	flat_load_dwordx4 v[62:65], v[88:89] offset:3840 nt
	s_add_u32 s12, s72, s4
	v_lshlrev_b32_e32 v71, 3, v0
	s_addc_u32 s13, s73, s5
	s_lshl_b64 s[4:5], s[6:7], 1
	v_lshl_add_u64 v[68:69], s[6:7], 2, v[136:137]
	v_cmp_eq_u64_e64 s[6:7], 0, v[136:137]
	v_lshrrev_b32_e32 v70, 3, v182
	v_and_b32_e32 v71, 56, v71
	s_add_u32 s12, s12, s4
	v_cndmask_b32_e64 v147, v69, 0, s[6:7]
	v_cndmask_b32_e64 v146, v68, 0, s[6:7]
	v_lshl_add_u32 v68, v91, 2, s14
	v_mul_u32_u24_e32 v69, 0x110, v90
	v_mul_u32_u24_e32 v72, 0x110, v71
	v_lshlrev_b32_e32 v73, 2, v70
	v_lshlrev_b32_e32 v70, 13, v70
	s_addc_u32 s13, s13, s5
	v_cmp_ne_u64_e64 s[4:5], 0, v[136:137]
	v_add3_u32 v149, s14, v72, v73
	v_and_b32_e32 v248, 7, v182
	v_mul_u32_u24_e32 v248, 0x770, v248
	v_sub_u32_e32 v149, v149, v248
	v_lshl_or_b32 v140, v71, 1, v70
	s_add_i32 s10, s15, 0xc60
	v_add_u32_e32 v150, v68, v69
	v_lshrrev_b32_e32 v248, 4, v182
	v_mul_u32_u24_e32 v248, 0x770, v248
	v_add_u32_e32 v150, v150, v248
	s_branch .LBB0_52
; #define GAS __attribute__((address_space(1)))
; #define LAS __attribute__((address_space(3)))
; __device__ __forceinline__ unsigned cvt_pk_bf16(float lo, float hi) { unsigned r; asm volatile("v_cvt_pk_bf16_f32 %0, %1, %2" : "=v"(r) : "v"(lo), "v"(hi)); return r; }
; #define LDS_WAIT() asm volatile("s_waitcnt lgkmcnt(0)" ::: "memory")
; __device__ __forceinline__ void p0_finish(const P0Item& it, const f32x4 (&w)[16], LAS float* scr, int lane) {
;     ...
;     const unsigned soff = (unsigned)(((lane >> 3) * it.K + 8 * (lane & 7)) * 2);
; #pragma unroll
;     for (int j = 0; j < 8; ++j) { const int n = (lane >> 3) + 8 * j, c = lane & 7; const LAS float* sp = scr + (8 * c) * 68 + n;
;         u32x4 o; o.x = cvt_pk_bf16(sp[0 * 68], sp[1 * 68]); o.y = cvt_pk_bf16(sp[2 * 68], sp[3 * 68]); o.z = cvt_pk_bf16(sp[4 * 68], sp[5 * 68]); o.w = cvt_pk_bf16(sp[6 * 68], sp[7 * 68]);
;         *(GAS u32x4*)((char*)(it.dst + (size_t)(8 * j) * it.K) + soff) = o; }
;     LDS_WAIT(); asm volatile("" ::: "memory");
.LBB0_51:
	s_or_b64 exec, exec, s[20:21]
	s_waitcnt vmcnt(0)
	ds_write_b128 v150, v[66:69] offset:10608
	s_waitcnt lgkmcnt(0)
	s_lshl_b64 s[16:17], s[16:17], 13
	s_add_u32 s16, s72, s16
	ds_read_b32 v66, v149
	ds_read_b32 v67, v149 offset:2176
	s_addc_u32 s17, s73, s17
	s_lshl_b64 s[14:15], s[14:15], 1
	s_waitcnt lgkmcnt(0)
	v_cvt_pk_bf16_f32 v66, v66, v67
	ds_read_b32 v68, v149 offset:4352
	ds_read_b32 v69, v149 offset:6528
	s_add_u32 s14, s16, s14
	s_waitcnt lgkmcnt(0)
	v_cvt_pk_bf16_f32 v67, v68, v69
	ds_read_b32 v68, v149 offset:8704
	ds_read_b32 v69, v149 offset:10880
	s_addc_u32 s15, s17, s15
	s_waitcnt lgkmcnt(0)
	v_cvt_pk_bf16_f32 v68, v68, v69
	ds_read_b32 v70, v149 offset:13056
	ds_read_b32 v71, v149 offset:15232
	s_waitcnt lgkmcnt(0)
	v_cvt_pk_bf16_f32 v69, v70, v71
	v_lshl_add_u64 v[72:73], s[14:15], 0, v[140:141]
	ds_read_b32 v70, v149 offset:32
	ds_read_b32 v71, v149 offset:2208
	global_store_dwordx4 v[72:73], v[66:69], off
	v_add_co_u32_e32 v74, vcc, s34, v72
	s_waitcnt lgkmcnt(0)
	v_cvt_pk_bf16_f32 v66, v70, v71
	ds_read_b32 v68, v149 offset:4384
	ds_read_b32 v69, v149 offset:6560
	s_waitcnt lgkmcnt(0)
	v_cvt_pk_bf16_f32 v67, v68, v69
	ds_read_b32 v68, v149 offset:8736
	ds_read_b32 v69, v149 offset:10912
	s_waitcnt lgkmcnt(0)
	v_cvt_pk_bf16_f32 v68, v68, v69
	ds_read_b32 v70, v149 offset:13088
	ds_read_b32 v71, v149 offset:15264
	s_waitcnt lgkmcnt(0)
	v_cvt_pk_bf16_f32 v69, v70, v71
	v_addc_co_u32_e32 v75, vcc, 0, v73, vcc
	ds_read_b32 v70, v149 offset:64
	ds_read_b32 v71, v149 offset:2240
	global_store_dwordx4 v[74:75], v[66:69], off
	v_add_co_u32_e32 v74, vcc, s35, v72
	s_waitcnt lgkmcnt(0)
	v_cvt_pk_bf16_f32 v66, v70, v71
	ds_read_b32 v68, v149 offset:4416
	ds_read_b32 v69, v149 offset:6592
	s_waitcnt lgkmcnt(0)
	v_cvt_pk_bf16_f32 v67, v68, v69
	ds_read_b32 v68, v149 offset:8768
	ds_read_b32 v69, v149 offset:10944
	s_waitcnt lgkmcnt(0)
	v_cvt_pk_bf16_f32 v68, v68, v69
	ds_read_b32 v70, v149 offset:13120
	ds_read_b32 v71, v149 offset:15296
	s_waitcnt lgkmcnt(0)
	v_cvt_pk_bf16_f32 v69, v70, v71
	v_addc_co_u32_e32 v75, vcc, 0, v73, vcc
	ds_read_b32 v70, v149 offset:96
	ds_read_b32 v71, v149 offset:2272
	global_store_dwordx4 v[74:75], v[66:69], off
	v_add_co_u32_e32 v74, vcc, s3, v72
	s_waitcnt lgkmcnt(0)
	v_cvt_pk_bf16_f32 v66, v70, v71
	ds_read_b32 v68, v149 offset:4448
	ds_read_b32 v69, v149 offset:6624
	s_waitcnt lgkmcnt(0)
	v_cvt_pk_bf16_f32 v67, v68, v69
	ds_read_b32 v68, v149 offset:8800
	ds_read_b32 v69, v149 offset:10976
	s_waitcnt lgkmcnt(0)
	v_cvt_pk_bf16_f32 v68, v68, v69
	ds_read_b32 v70, v149 offset:13152
	ds_read_b32 v71, v149 offset:15328
	s_waitcnt lgkmcnt(0)
	v_cvt_pk_bf16_f32 v69, v70, v71
	v_addc_co_u32_e32 v75, vcc, 0, v73, vcc
	ds_read_b32 v70, v149 offset:128
	ds_read_b32 v71, v149 offset:2304
	global_store_dwordx4 v[74:75], v[66:69], off
	v_add_co_u32_e32 v74, vcc, s36, v72
	s_waitcnt lgkmcnt(0)
	v_cvt_pk_bf16_f32 v66, v70, v71
	ds_read_b32 v68, v149 offset:4480
	ds_read_b32 v69, v149 offset:6656
	s_waitcnt lgkmcnt(0)
	v_cvt_pk_bf16_f32 v67, v68, v69
	ds_read_b32 v68, v149 offset:8832
	ds_read_b32 v69, v149 offset:11008
	s_waitcnt lgkmcnt(0)
	v_cvt_pk_bf16_f32 v68, v68, v69
	ds_read_b32 v70, v149 offset:13184
	ds_read_b32 v71, v149 offset:15360
	s_waitcnt lgkmcnt(0)
	v_cvt_pk_bf16_f32 v69, v70, v71
	v_addc_co_u32_e32 v75, vcc, 0, v73, vcc
	ds_read_b32 v70, v149 offset:160
	ds_read_b32 v71, v149 offset:2336
	global_store_dwordx4 v[74:75], v[66:69], off
	v_add_co_u32_e32 v74, vcc, s37, v72
	s_waitcnt lgkmcnt(0)
	v_cvt_pk_bf16_f32 v66, v70, v71
	ds_read_b32 v68, v149 offset:4512
	ds_read_b32 v69, v149 offset:6688
	s_waitcnt lgkmcnt(0)
	v_cvt_pk_bf16_f32 v67, v68, v69
	ds_read_b32 v68, v149 offset:8864
	ds_read_b32 v69, v149 offset:11040
	s_waitcnt lgkmcnt(0)
	v_cvt_pk_bf16_f32 v68, v68, v69
	ds_read_b32 v70, v149 offset:13216
	ds_read_b32 v71, v149 offset:15392
	s_waitcnt lgkmcnt(0)
	v_cvt_pk_bf16_f32 v69, v70, v71
	v_addc_co_u32_e32 v75, vcc, 0, v73, vcc
	ds_read_b32 v70, v149 offset:192
	ds_read_b32 v71, v149 offset:2368
	global_store_dwordx4 v[74:75], v[66:69], off
	v_add_co_u32_e32 v74, vcc, s22, v72
	s_waitcnt lgkmcnt(0)
	v_cvt_pk_bf16_f32 v66, v70, v71
	ds_read_b32 v68, v149 offset:4544
	ds_read_b32 v69, v149 offset:6720
	s_waitcnt lgkmcnt(0)
	v_cvt_pk_bf16_f32 v67, v68, v69
	ds_read_b32 v68, v149 offset:8896
	ds_read_b32 v69, v149 offset:11072
	s_waitcnt lgkmcnt(0)
	v_cvt_pk_bf16_f32 v68, v68, v69
	ds_read_b32 v70, v149 offset:13248
	ds_read_b32 v71, v149 offset:15424
	s_waitcnt lgkmcnt(0)
	v_cvt_pk_bf16_f32 v69, v70, v71
	v_addc_co_u32_e32 v75, vcc, 0, v73, vcc
	ds_read_b32 v70, v149 offset:224
	ds_read_b32 v71, v149 offset:2400
	global_store_dwordx4 v[74:75], v[66:69], off
	v_add_co_u32_e32 v72, vcc, 0x70000, v72
	s_waitcnt lgkmcnt(0)
	v_cvt_pk_bf16_f32 v66, v70, v71
	ds_read_b32 v68, v149 offset:4576
	ds_read_b32 v69, v149 offset:6752
	s_waitcnt lgkmcnt(0)
	v_cvt_pk_bf16_f32 v67, v68, v69
	ds_read_b32 v68, v149 offset:8928
	ds_read_b32 v69, v149 offset:11104
	v_addc_co_u32_e32 v73, vcc, 0, v73, vcc
	s_waitcnt lgkmcnt(0)
	v_cvt_pk_bf16_f32 v68, v68, v69
	ds_read_b32 v70, v149 offset:13280
	ds_read_b32 v71, v149 offset:15456
	s_waitcnt lgkmcnt(0)
	v_cvt_pk_bf16_f32 v69, v70, v71
	global_store_dwordx4 v[72:73], v[66:69], off
	s_waitcnt lgkmcnt(0)
	s_add_i32 s11, s11, 2
	s_andn2_b64 vcc, exec, s[18:19]
	s_addk_i32 s10, 0xc00
	s_cbranch_vccz .LBB0_62
; #define LAS __attribute__((address_space(3)))
; __device__ __forceinline__ void p0_load(const P0Item& it, f32x4 (&w)[16], int lane) {
;     const unsigned voff = (unsigned)(((lane >> 4) * it.ldw + (lane & 15) * 4) * 4);
; #pragma unroll
;     for (int i = 0; i < 16; ++i) w[i] = __builtin_nontemporal_load((const f32x4*)((const char*)(it.src + (size_t)(4 * i) * it.ldw) + voff));
; }
; __device__ __forceinline__ void p0_finish(const P0Item& it, const f32x4 (&w)[16], LAS float* scr, int lane) {
;     const int c4 = (lane & 15) * 4, kr = lane >> 4;
;     if (it.gain) { const unsigned goff = (unsigned)(kr * 4);
; #pragma unroll
;         for (int i = 0; i < 16; ++i) { const float g = *(const float*)((const char*)(it.gain + 4 * i) + goff); *(LAS f32x4*)(scr + (kr + 4 * i) * 68 + c4) = w[i] * g; } }
; template <class F> __device__ __forceinline__ void p0_pipe(int n, F desc, LAS float* scr, int lane) {
;     ...
;     for (int j = 0; j < n; j += 2) {
;         const bool hb_ = j + 1 < n; if (hb_) { b = desc(j + 1); p0_load(b, w1, lane); }
;         p0_finish(a, w0, scr, lane);
;         if (!hb_) break;
;         if (j + 2 < n) { a = desc(j + 2); p0_load(a, w0, lane); }
.LBB0_52:
	s_add_i32 s14, s10, 0xfffffa00
	s_mul_hi_i32 s15, s14, 0x2aaaaaab
	s_lshr_b32 s16, s15, 31
	s_ashr_i32 s15, s15, 5
	s_add_i32 s15, s15, s16
	s_mul_i32 s16, s15, 0xc0
	s_sub_i32 s16, s14, s16
	s_lshl_b32 s14, s15, 6
	s_lshl_b32 s16, s16, 6
	v_mad_i64_i32 v[66:67], s[18:19], s14, v148, v[142:143]
	s_ashr_i32 s17, s16, 31
	v_lshl_add_u64 v[66:67], s[16:17], 2, v[66:67]
	v_lshl_add_u64 v[66:67], v[66:67], 0, v[134:135]
	v_add_co_u32_e32 v68, vcc, s3, v66
	s_nop 1
	v_addc_co_u32_e32 v69, vcc, 0, v67, vcc
	flat_load_dwordx4 v[126:129], v[66:67] nt
	flat_load_dwordx4 v[122:125], v[68:69] offset:256 nt
	v_add_co_u32_e32 v68, vcc, s22, v66
	s_nop 1
	v_addc_co_u32_e32 v69, vcc, 0, v67, vcc
	v_add_co_u32_e32 v70, vcc, s23, v66
	s_nop 1
	v_addc_co_u32_e32 v71, vcc, 0, v67, vcc
	flat_load_dwordx4 v[118:121], v[68:69] offset:512 nt
	flat_load_dwordx4 v[114:117], v[70:71] offset:768 nt
	v_add_co_u32_e32 v68, vcc, s24, v66
	s_nop 1
	v_addc_co_u32_e32 v69, vcc, 0, v67, vcc
	v_add_co_u32_e32 v70, vcc, s25, v66
	s_nop 1
	v_addc_co_u32_e32 v71, vcc, 0, v67, vcc
	flat_load_dwordx4 v[110:113], v[68:69] offset:1024 nt
	flat_load_dwordx4 v[106:109], v[70:71] offset:1280 nt
	v_add_co_u32_e32 v68, vcc, s26, v66
	s_nop 1
	v_addc_co_u32_e32 v69, vcc, 0, v67, vcc
	v_add_co_u32_e32 v70, vcc, s27, v66
	s_nop 1
	v_addc_co_u32_e32 v71, vcc, 0, v67, vcc
	flat_load_dwordx4 v[102:105], v[68:69] offset:1536 nt
	flat_load_dwordx4 v[98:101], v[70:71] offset:1792 nt
	v_add_co_u32_e32 v68, vcc, s28, v66
	s_nop 1
	v_addc_co_u32_e32 v69, vcc, 0, v67, vcc
	v_add_co_u32_e32 v70, vcc, s29, v66
	s_nop 1
	v_addc_co_u32_e32 v71, vcc, 0, v67, vcc
	flat_load_dwordx4 v[94:97], v[68:69] offset:2048 nt
	flat_load_dwordx4 v[90:93], v[70:71] offset:2304 nt
	v_add_co_u32_e32 v68, vcc, s30, v66
	s_nop 1
	v_addc_co_u32_e32 v69, vcc, 0, v67, vcc
	v_add_co_u32_e32 v70, vcc, s31, v66
	s_nop 1
	v_addc_co_u32_e32 v71, vcc, 0, v67, vcc
	flat_load_dwordx4 v[86:89], v[68:69] offset:2560 nt
	flat_load_dwordx4 v[82:85], v[70:71] offset:2816 nt
	v_add_co_u32_e32 v68, vcc, s33, v66
	s_nop 1
	v_addc_co_u32_e32 v69, vcc, 0, v67, vcc
	v_add_co_u32_e32 v70, vcc, 0x270000, v66
	s_nop 1
	v_addc_co_u32_e32 v71, vcc, 0, v67, vcc
	flat_load_dwordx4 v[78:81], v[68:69] offset:3072 nt
	flat_load_dwordx4 v[74:77], v[70:71] offset:3328 nt
	v_add_co_u32_e32 v68, vcc, 0x2a0000, v66
	s_nop 1
	v_addc_co_u32_e32 v69, vcc, 0, v67, vcc
	v_add_co_u32_e32 v66, vcc, 0x2d0000, v66
	s_nop 1
	v_addc_co_u32_e32 v67, vcc, 0, v67, vcc
	flat_load_dwordx4 v[70:73], v[68:69] offset:3584 nt
	s_nop 0
	flat_load_dwordx4 v[66:69], v[66:67] offset:3840 nt
	v_cmp_ne_u64_e32 vcc, 0, v[146:147]
	s_and_saveexec_b64 s[18:19], vcc
	s_xor_b64 s[18:19], exec, s[18:19]
	s_cbranch_execz .LBB0_54
	v_lshl_add_u64 v[152:153], v[146:147], 0, v[138:139]
	flat_load_dword v130, v[152:153]
	s_waitcnt vmcnt(0) lgkmcnt(0)
	v_pk_mul_f32 v[132:133], v[4:5], v[130:131] op_sel_hi:[1,0]
	v_pk_mul_f32 v[130:131], v[2:3], v[130:131] op_sel_hi:[1,0]
	ds_write_b128 v150, v[130:133]
	flat_load_dword v130, v[152:153] offset:16
	s_waitcnt vmcnt(0) lgkmcnt(0)
	v_pk_mul_f32 v[132:133], v[8:9], v[130:131] op_sel_hi:[1,0]
	v_pk_mul_f32 v[130:131], v[6:7], v[130:131] op_sel_hi:[1,0]
	ds_write_b128 v150, v[130:133] offset:8704
	flat_load_dword v130, v[152:153] offset:32
	s_waitcnt vmcnt(0) lgkmcnt(0)
	v_pk_mul_f32 v[132:133], v[12:13], v[130:131] op_sel_hi:[1,0]
	v_pk_mul_f32 v[130:131], v[10:11], v[130:131] op_sel_hi:[1,0]
	ds_write_b128 v150, v[130:133] offset:272
	flat_load_dword v130, v[152:153] offset:48
	s_waitcnt vmcnt(0) lgkmcnt(0)
	v_pk_mul_f32 v[132:133], v[16:17], v[130:131] op_sel_hi:[1,0]
	v_pk_mul_f32 v[130:131], v[14:15], v[130:131] op_sel_hi:[1,0]
	ds_write_b128 v150, v[130:133] offset:8976
	flat_load_dword v130, v[152:153] offset:64
	s_waitcnt vmcnt(0) lgkmcnt(0)
	v_pk_mul_f32 v[132:133], v[20:21], v[130:131] op_sel_hi:[1,0]
	v_pk_mul_f32 v[130:131], v[18:19], v[130:131] op_sel_hi:[1,0]
	ds_write_b128 v150, v[130:133] offset:544
	flat_load_dword v130, v[152:153] offset:80
	s_waitcnt vmcnt(0) lgkmcnt(0)
	v_pk_mul_f32 v[132:133], v[24:25], v[130:131] op_sel_hi:[1,0]
	v_pk_mul_f32 v[130:131], v[22:23], v[130:131] op_sel_hi:[1,0]
	ds_write_b128 v150, v[130:133] offset:9248
	flat_load_dword v130, v[152:153] offset:96
	s_waitcnt vmcnt(0) lgkmcnt(0)
	v_pk_mul_f32 v[132:133], v[28:29], v[130:131] op_sel_hi:[1,0]
	v_pk_mul_f32 v[130:131], v[26:27], v[130:131] op_sel_hi:[1,0]
	ds_write_b128 v150, v[130:133] offset:816
	flat_load_dword v130, v[152:153] offset:112
	s_waitcnt vmcnt(0) lgkmcnt(0)
	v_pk_mul_f32 v[132:133], v[32:33], v[130:131] op_sel_hi:[1,0]
	v_pk_mul_f32 v[130:131], v[30:31], v[130:131] op_sel_hi:[1,0]
	ds_write_b128 v150, v[130:133] offset:9520
	flat_load_dword v130, v[152:153] offset:128
	s_waitcnt vmcnt(0) lgkmcnt(0)
	v_pk_mul_f32 v[132:133], v[36:37], v[130:131] op_sel_hi:[1,0]
	v_pk_mul_f32 v[130:131], v[34:35], v[130:131] op_sel_hi:[1,0]
	ds_write_b128 v150, v[130:133] offset:1088
	flat_load_dword v130, v[152:153] offset:144
	s_waitcnt vmcnt(0) lgkmcnt(0)
	v_pk_mul_f32 v[132:133], v[40:41], v[130:131] op_sel_hi:[1,0]
	v_pk_mul_f32 v[130:131], v[38:39], v[130:131] op_sel_hi:[1,0]
	ds_write_b128 v150, v[130:133] offset:9792
	flat_load_dword v130, v[152:153] offset:160
	s_waitcnt vmcnt(0) lgkmcnt(0)
	v_pk_mul_f32 v[132:133], v[44:45], v[130:131] op_sel_hi:[1,0]
	v_pk_mul_f32 v[130:131], v[42:43], v[130:131] op_sel_hi:[1,0]
	ds_write_b128 v150, v[130:133] offset:1360
	flat_load_dword v130, v[152:153] offset:176
	s_waitcnt vmcnt(0) lgkmcnt(0)
	v_pk_mul_f32 v[132:133], v[48:49], v[130:131] op_sel_hi:[1,0]
	v_pk_mul_f32 v[130:131], v[46:47], v[130:131] op_sel_hi:[1,0]
	ds_write_b128 v150, v[130:133] offset:10064
	flat_load_dword v130, v[152:153] offset:192
	s_waitcnt vmcnt(0) lgkmcnt(0)
	v_pk_mul_f32 v[132:133], v[52:53], v[130:131] op_sel_hi:[1,0]
	v_pk_mul_f32 v[130:131], v[50:51], v[130:131] op_sel_hi:[1,0]
	ds_write_b128 v150, v[130:133] offset:1632
	flat_load_dword v130, v[152:153] offset:208
	s_waitcnt vmcnt(0) lgkmcnt(0)
	v_pk_mul_f32 v[132:133], v[56:57], v[130:131] op_sel_hi:[1,0]
	v_pk_mul_f32 v[130:131], v[54:55], v[130:131] op_sel_hi:[1,0]
	ds_write_b128 v150, v[130:133] offset:10336
	flat_load_dword v130, v[152:153] offset:224
	s_waitcnt vmcnt(0) lgkmcnt(0)
	v_pk_mul_f32 v[132:133], v[60:61], v[130:131] op_sel_hi:[1,0]
	v_pk_mul_f32 v[130:131], v[58:59], v[130:131] op_sel_hi:[1,0]
	ds_write_b128 v150, v[130:133] offset:1904
	flat_load_dword v130, v[152:153] offset:240
	s_waitcnt vmcnt(0) lgkmcnt(0)
	v_pk_mul_f32 v[132:133], v[64:65], v[130:131] op_sel_hi:[1,0]
	v_pk_mul_f32 v[130:131], v[62:63], v[130:131] op_sel_hi:[1,0]
; #define GAS __attribute__((address_space(1)))
; #define LAS __attribute__((address_space(3)))
; __device__ __forceinline__ unsigned cvt_pk_bf16(float lo, float hi) { unsigned r; asm volatile("v_cvt_pk_bf16_f32 %0, %1, %2" : "=v"(r) : "v"(lo), "v"(hi)); return r; }
; #define LDS_WAIT() asm volatile("s_waitcnt lgkmcnt(0)" ::: "memory")
; __device__ __forceinline__ void p0_finish(const P0Item& it, const f32x4 (&w)[16], LAS float* scr, int lane) {
;     ...
;     else {
; #pragma unroll
;         for (int i = 0; i < 16; ++i) *(LAS f32x4*)(scr + (kr + 4 * i) * 68 + c4) = w[i]; }
;     LDS_WAIT(); asm volatile("" ::: "memory");
;     const unsigned soff = (unsigned)(((lane >> 3) * it.K + 8 * (lane & 7)) * 2);
; #pragma unroll
;     for (int j = 0; j < 8; ++j) { const int n = (lane >> 3) + 8 * j, c = lane & 7; const LAS float* sp = scr + (8 * c) * 68 + n;
;         u32x4 o; o.x = cvt_pk_bf16(sp[0 * 68], sp[1 * 68]); o.y = cvt_pk_bf16(sp[2 * 68], sp[3 * 68]); o.z = cvt_pk_bf16(sp[4 * 68], sp[5 * 68]); o.w = cvt_pk_bf16(sp[6 * 68], sp[7 * 68]);
;         *(GAS u32x4*)((char*)(it.dst + (size_t)(8 * j) * it.K) + soff) = o; }
;     LDS_WAIT(); asm volatile("" ::: "memory");
.LBB0_54:
	s_andn2_saveexec_b64 s[18:19], s[18:19]
	s_cbranch_execz .LBB0_56
	s_waitcnt vmcnt(0) lgkmcnt(0)
	v_mov_b64_e32 v[132:133], v[64:65]
	v_mov_b64_e32 v[130:131], v[62:63]
	ds_write_b128 v150, v[2:5]
	ds_write_b128 v150, v[6:9] offset:8704
	ds_write_b128 v150, v[10:13] offset:272
	ds_write_b128 v150, v[14:17] offset:8976
	ds_write_b128 v150, v[18:21] offset:544
	ds_write_b128 v150, v[22:25] offset:9248
	ds_write_b128 v150, v[26:29] offset:816
	ds_write_b128 v150, v[30:33] offset:9520
	ds_write_b128 v150, v[34:37] offset:1088
	ds_write_b128 v150, v[38:41] offset:9792
	ds_write_b128 v150, v[42:45] offset:1360
	ds_write_b128 v150, v[46:49] offset:10064
	ds_write_b128 v150, v[50:53] offset:1632
	ds_write_b128 v150, v[54:57] offset:10336
	ds_write_b128 v150, v[58:61] offset:1904
.LBB0_56:
	s_or_b64 exec, exec, s[18:19]
	ds_write_b128 v150, v[130:133] offset:10608
	s_waitcnt lgkmcnt(0)
	ds_read_b32 v130, v149
	ds_read_b32 v131, v149 offset:2176
	s_waitcnt lgkmcnt(0)
	v_cvt_pk_bf16_f32 v152, v130, v131
	ds_read_b32 v132, v149 offset:4352
	ds_read_b32 v133, v149 offset:6528
	v_add_u32_e32 v130, 0x400, v149
	s_waitcnt lgkmcnt(0)
	v_cvt_pk_bf16_f32 v153, v132, v133
	ds_read_b32 v132, v149 offset:8704
	ds_read_b32 v133, v149 offset:10880
	s_waitcnt lgkmcnt(0)
	v_cvt_pk_bf16_f32 v154, v132, v133
	ds_read_b32 v132, v149 offset:13056
	ds_read_b32 v133, v149 offset:15232
	s_waitcnt lgkmcnt(0)
	v_cvt_pk_bf16_f32 v155, v132, v133
	ds_read_b32 v132, v149 offset:32
	ds_read_b32 v133, v149 offset:2208
	v_lshl_add_u64 v[156:157], s[12:13], 0, v[140:141]
	global_store_dwordx4 v[156:157], v[152:155], off
	v_add_co_u32_e32 v158, vcc, s34, v156
	s_waitcnt lgkmcnt(0)
	v_cvt_pk_bf16_f32 v152, v132, v133
	ds_read_b32 v132, v149 offset:4384
	ds_read_b32 v133, v149 offset:6560
	s_waitcnt lgkmcnt(0)
	v_cvt_pk_bf16_f32 v153, v132, v133
	ds_read_b32 v132, v149 offset:8736
	ds_read_b32 v133, v149 offset:10912
	s_waitcnt lgkmcnt(0)
	v_cvt_pk_bf16_f32 v154, v132, v133
	ds_read_b32 v132, v149 offset:13088
	ds_read_b32 v133, v149 offset:15264
	s_waitcnt lgkmcnt(0)
	v_cvt_pk_bf16_f32 v155, v132, v133
	ds_read_b32 v132, v149 offset:64
	ds_read_b32 v133, v149 offset:2240
	v_addc_co_u32_e32 v159, vcc, 0, v157, vcc
	global_store_dwordx4 v[158:159], v[152:155], off
	v_add_co_u32_e32 v158, vcc, s35, v156
	s_waitcnt lgkmcnt(0)
	v_cvt_pk_bf16_f32 v152, v132, v133
	ds_read_b32 v132, v149 offset:4416
	ds_read_b32 v133, v149 offset:6592
	s_waitcnt lgkmcnt(0)
	v_cvt_pk_bf16_f32 v153, v132, v133
	ds_read_b32 v132, v149 offset:8768
	ds_read_b32 v133, v149 offset:10944
	s_waitcnt lgkmcnt(0)
	v_cvt_pk_bf16_f32 v154, v132, v133
	ds_read_b32 v132, v149 offset:13120
	ds_read_b32 v133, v149 offset:15296
	s_waitcnt lgkmcnt(0)
	v_cvt_pk_bf16_f32 v155, v132, v133
	ds_read_b32 v132, v149 offset:96
	ds_read_b32 v133, v149 offset:2272
	v_addc_co_u32_e32 v159, vcc, 0, v157, vcc
	global_store_dwordx4 v[158:159], v[152:155], off
	v_add_co_u32_e32 v158, vcc, s3, v156
	s_waitcnt lgkmcnt(0)
	v_cvt_pk_bf16_f32 v152, v132, v133
	ds_read_b32 v132, v149 offset:4448
	ds_read_b32 v133, v149 offset:6624
	s_waitcnt lgkmcnt(0)
	v_cvt_pk_bf16_f32 v153, v132, v133
	ds_read_b32 v132, v149 offset:8800
	ds_read_b32 v133, v149 offset:10976
	s_waitcnt lgkmcnt(0)
	v_cvt_pk_bf16_f32 v154, v132, v133
	ds_read_b32 v132, v149 offset:13152
	ds_read_b32 v133, v149 offset:15328
	s_waitcnt lgkmcnt(0)
	v_cvt_pk_bf16_f32 v155, v132, v133
	ds_read_b32 v132, v149 offset:128
	ds_read_b32 v133, v149 offset:2304
	v_addc_co_u32_e32 v159, vcc, 0, v157, vcc
	global_store_dwordx4 v[158:159], v[152:155], off
	v_add_co_u32_e32 v158, vcc, s36, v156
	s_waitcnt lgkmcnt(0)
	v_cvt_pk_bf16_f32 v152, v132, v133
	ds_read_b32 v132, v149 offset:4480
	ds_read_b32 v133, v149 offset:6656
	s_waitcnt lgkmcnt(0)
	v_cvt_pk_bf16_f32 v153, v132, v133
	ds_read_b32 v132, v149 offset:8832
	ds_read_b32 v133, v149 offset:11008
	s_waitcnt lgkmcnt(0)
	v_cvt_pk_bf16_f32 v154, v132, v133
	ds_read_b32 v132, v149 offset:13184
	ds_read_b32 v133, v149 offset:15360
	s_waitcnt lgkmcnt(0)
	v_cvt_pk_bf16_f32 v155, v132, v133
	ds_read_b32 v132, v149 offset:160
	ds_read_b32 v133, v149 offset:2336
	v_addc_co_u32_e32 v159, vcc, 0, v157, vcc
	global_store_dwordx4 v[158:159], v[152:155], off
	v_add_u32_e32 v131, 0x600, v149
	v_add_co_u32_e32 v158, vcc, s37, v156
	s_waitcnt lgkmcnt(0)
	v_cvt_pk_bf16_f32 v152, v132, v133
	ds_read_b32 v132, v149 offset:4512
	ds_read_b32 v133, v149 offset:6688
	s_waitcnt lgkmcnt(0)
	v_cvt_pk_bf16_f32 v153, v132, v133
	ds_read_b32 v132, v149 offset:8864
	ds_read_b32 v133, v149 offset:11040
	s_waitcnt lgkmcnt(0)
	v_cvt_pk_bf16_f32 v154, v132, v133
	ds_read_b32 v132, v149 offset:13216
	ds_read_b32 v133, v149 offset:15392
	s_waitcnt lgkmcnt(0)
	v_cvt_pk_bf16_f32 v155, v132, v133
	ds_read_b32 v132, v149 offset:192
	ds_read_b32 v133, v149 offset:2368
	v_addc_co_u32_e32 v159, vcc, 0, v157, vcc
	global_store_dwordx4 v[158:159], v[152:155], off
	v_add_co_u32_e32 v160, vcc, s22, v156
	s_waitcnt lgkmcnt(0)
	v_cvt_pk_bf16_f32 v152, v132, v133
	ds_read_b32 v132, v149 offset:4544
	ds_read_b32 v133, v149 offset:6720
	s_waitcnt lgkmcnt(0)
	v_cvt_pk_bf16_f32 v153, v132, v133
	ds_read_b32 v132, v149 offset:8896
	ds_read_b32 v133, v149 offset:11072
	s_waitcnt lgkmcnt(0)
	v_cvt_pk_bf16_f32 v154, v132, v133
	ds_read_b32 v158, v149 offset:13248
	ds_read_b32 v159, v149 offset:15424
	v_add_u32_e32 v132, 0x200, v149
	s_waitcnt lgkmcnt(0)
	v_cvt_pk_bf16_f32 v155, v158, v159
	v_addc_co_u32_e32 v161, vcc, 0, v157, vcc
	ds_read_b32 v158, v149 offset:224
	ds_read_b32 v159, v149 offset:2400
	global_store_dwordx4 v[160:161], v[152:155], off
	v_add_co_u32_e32 v156, vcc, 0x70000, v156
	s_waitcnt lgkmcnt(0)
	v_cvt_pk_bf16_f32 v152, v158, v159
	ds_read_b32 v154, v149 offset:4576
	ds_read_b32 v155, v149 offset:6752
	s_waitcnt lgkmcnt(0)
	v_cvt_pk_bf16_f32 v153, v154, v155
	ds_read_b32 v154, v149 offset:8928
	ds_read_b32 v155, v149 offset:11104
	v_addc_co_u32_e32 v157, vcc, 0, v157, vcc
	s_waitcnt lgkmcnt(0)
	v_cvt_pk_bf16_f32 v154, v154, v155
	ds_read_b32 v158, v149 offset:13280
	ds_read_b32 v159, v149 offset:15456
	s_waitcnt lgkmcnt(0)
	v_cvt_pk_bf16_f32 v155, v158, v159
	global_store_dwordx4 v[156:157], v[152:155], off
	s_waitcnt lgkmcnt(0)
	s_cmp_gt_u32 s11, 5
	s_cselect_b64 s[18:19], -1, 0
	s_and_b64 vcc, exec, s[18:19]
	s_cbranch_vccz .LBB0_59
	s_ashr_i32 s15, s14, 31
	s_and_saveexec_b64 s[20:21], s[4:5]
	s_xor_b64 s[20:21], exec, s[20:21]
	s_cbranch_execnz .LBB0_60

; #define LAS __attribute__((address_space(3)))
; __device__ __forceinline__ void p0_finish(const P0Item& it, const f32x4 (&w)[16], LAS float* scr, int lane) {
;     ...
;     if (it.gain) { const unsigned goff = (unsigned)(kr * 4);
; #pragma unroll
;         for (int i = 0; i < 16; ++i) { const float g = *(const float*)((const char*)(it.gain + 4 * i) + goff); *(LAS f32x4*)(scr + (kr + 4 * i) * 68 + c4) = w[i] * g; } }
;     else {
; #pragma unroll
;         for (int i = 0; i < 16; ++i) *(LAS f32x4*)(scr + (kr + 4 * i) * 68 + c4) = w[i]; }
.LBB0_60:
	v_lshl_add_u64 v[152:153], s[14:15], 2, v[144:145]
	flat_load_dword v154, v[152:153]
	s_waitcnt vmcnt(0) lgkmcnt(0)
	v_pk_mul_f32 v[128:129], v[128:129], v[154:155] op_sel_hi:[1,0]
	v_pk_mul_f32 v[126:127], v[126:127], v[154:155] op_sel_hi:[1,0]
	ds_write_b128 v150, v[126:129]
	flat_load_dword v126, v[152:153] offset:16
	s_waitcnt vmcnt(0) lgkmcnt(0)
	v_pk_mul_f32 v[124:125], v[124:125], v[126:127] op_sel_hi:[1,0]
	v_pk_mul_f32 v[122:123], v[122:123], v[126:127] op_sel_hi:[1,0]
	ds_write_b128 v150, v[122:125] offset:8704
	flat_load_dword v122, v[152:153] offset:32
	s_waitcnt vmcnt(0) lgkmcnt(0)
	v_pk_mul_f32 v[120:121], v[120:121], v[122:123] op_sel_hi:[1,0]
	v_pk_mul_f32 v[118:119], v[118:119], v[122:123] op_sel_hi:[1,0]
	ds_write_b128 v150, v[118:121] offset:272
	flat_load_dword v118, v[152:153] offset:48
	s_waitcnt vmcnt(0) lgkmcnt(0)
	v_pk_mul_f32 v[116:117], v[116:117], v[118:119] op_sel_hi:[1,0]
	v_pk_mul_f32 v[114:115], v[114:115], v[118:119] op_sel_hi:[1,0]
	ds_write_b128 v150, v[114:117] offset:8976
	flat_load_dword v114, v[152:153] offset:64
	s_waitcnt vmcnt(0) lgkmcnt(0)
	v_pk_mul_f32 v[112:113], v[112:113], v[114:115] op_sel_hi:[1,0]
	v_pk_mul_f32 v[110:111], v[110:111], v[114:115] op_sel_hi:[1,0]
	ds_write_b128 v150, v[110:113] offset:544
	flat_load_dword v110, v[152:153] offset:80
	s_waitcnt vmcnt(0) lgkmcnt(0)
	v_pk_mul_f32 v[108:109], v[108:109], v[110:111] op_sel_hi:[1,0]
	v_pk_mul_f32 v[106:107], v[106:107], v[110:111] op_sel_hi:[1,0]
	ds_write_b128 v150, v[106:109] offset:9248
	flat_load_dword v106, v[152:153] offset:96
	s_waitcnt vmcnt(0) lgkmcnt(0)
	v_pk_mul_f32 v[104:105], v[104:105], v[106:107] op_sel_hi:[1,0]
	v_pk_mul_f32 v[102:103], v[102:103], v[106:107] op_sel_hi:[1,0]
	ds_write_b128 v150, v[102:105] offset:816
	flat_load_dword v102, v[152:153] offset:112
	s_waitcnt vmcnt(0) lgkmcnt(0)
	v_pk_mul_f32 v[100:101], v[100:101], v[102:103] op_sel_hi:[1,0]
	v_pk_mul_f32 v[98:99], v[98:99], v[102:103] op_sel_hi:[1,0]
	ds_write_b128 v150, v[98:101] offset:9520
	flat_load_dword v98, v[152:153] offset:128
	s_waitcnt vmcnt(0) lgkmcnt(0)
	v_pk_mul_f32 v[96:97], v[96:97], v[98:99] op_sel_hi:[1,0]
	v_pk_mul_f32 v[94:95], v[94:95], v[98:99] op_sel_hi:[1,0]
	ds_write_b128 v150, v[94:97] offset:1088
	flat_load_dword v94, v[152:153] offset:144
	s_waitcnt vmcnt(0) lgkmcnt(0)
	v_pk_mul_f32 v[92:93], v[92:93], v[94:95] op_sel_hi:[1,0]
	v_pk_mul_f32 v[90:91], v[90:91], v[94:95] op_sel_hi:[1,0]
	ds_write_b128 v150, v[90:93] offset:9792
	flat_load_dword v90, v[152:153] offset:160
	s_waitcnt vmcnt(0) lgkmcnt(0)
	v_pk_mul_f32 v[88:89], v[88:89], v[90:91] op_sel_hi:[1,0]
	v_pk_mul_f32 v[86:87], v[86:87], v[90:91] op_sel_hi:[1,0]
	ds_write_b128 v150, v[86:89] offset:1360
	flat_load_dword v86, v[152:153] offset:176
	s_waitcnt vmcnt(0) lgkmcnt(0)
	v_pk_mul_f32 v[84:85], v[84:85], v[86:87] op_sel_hi:[1,0]
	v_pk_mul_f32 v[82:83], v[82:83], v[86:87] op_sel_hi:[1,0]
	ds_write_b128 v150, v[82:85] offset:10064
	flat_load_dword v82, v[152:153] offset:192
	s_waitcnt vmcnt(0) lgkmcnt(0)
	v_pk_mul_f32 v[80:81], v[80:81], v[82:83] op_sel_hi:[1,0]
	v_pk_mul_f32 v[78:79], v[78:79], v[82:83] op_sel_hi:[1,0]
	ds_write_b128 v150, v[78:81] offset:1632
	flat_load_dword v78, v[152:153] offset:208
	s_waitcnt vmcnt(0) lgkmcnt(0)
	v_pk_mul_f32 v[76:77], v[76:77], v[78:79] op_sel_hi:[1,0]
	v_pk_mul_f32 v[74:75], v[74:75], v[78:79] op_sel_hi:[1,0]
	ds_write_b128 v150, v[74:77] offset:10336
	flat_load_dword v74, v[152:153] offset:224
	s_waitcnt vmcnt(0) lgkmcnt(0)
	v_pk_mul_f32 v[72:73], v[72:73], v[74:75] op_sel_hi:[1,0]
	v_pk_mul_f32 v[70:71], v[70:71], v[74:75] op_sel_hi:[1,0]
	ds_write_b128 v150, v[70:73] offset:1904
	flat_load_dword v70, v[152:153] offset:240
	s_waitcnt vmcnt(0) lgkmcnt(0)
	v_pk_mul_f32 v[68:69], v[68:69], v[70:71] op_sel_hi:[1,0]
	v_pk_mul_f32 v[66:67], v[66:67], v[70:71] op_sel_hi:[1,0]
	s_andn2_saveexec_b64 s[20:21], s[20:21]
	s_cbranch_execz .LBB0_51
.LBB0_61:
	s_waitcnt vmcnt(0)
	ds_write_b128 v150, v[126:129]
	ds_write_b128 v150, v[122:125] offset:8704
	ds_write_b128 v150, v[118:121] offset:272
	ds_write_b128 v150, v[114:117] offset:8976
	ds_write_b128 v150, v[110:113] offset:544
	ds_write_b128 v150, v[106:109] offset:9248
	ds_write_b128 v150, v[102:105] offset:816
	ds_write_b128 v150, v[98:101] offset:9520
	ds_write_b128 v150, v[94:97] offset:1088
	ds_write_b128 v150, v[90:93] offset:9792
	ds_write_b128 v150, v[86:89] offset:1360
	ds_write_b128 v150, v[82:85] offset:10064
	ds_write_b128 v150, v[78:81] offset:1632
	ds_write_b128 v150, v[74:77] offset:10336
	ds_write_b128 v150, v[70:73] offset:1904
	s_branch .LBB0_51
